# P2 math: register copies left by the packed-op split removed by copy propagation (54 v_mov)
# speedup vs baseline: 1.0079x; 1.0079x over previous
.LBB0_347:
	v_mul_f32_e32 v18, 0x3e38aa3b, v18
	v_exp_f32_e32 v18, v18
	s_nop 7
	v_mul_f32_e32 v2, 0x3e38aa3b, v2
	v_exp_f32_e32 v2, v2
	v_mul_f32_e32 v3, 0x3e38aa3b, v3
	v_add_f32_e32 v18, 1.0, v18
	v_exp_f32_e32 v3, v3
	v_add_f32_e32 v66, 1.0, v2
	v_rcp_f32_e32 v2, v18
	v_mul_f32_e32 v18, 0x3e38aa3b, v19
	v_mul_f32_e32 v19, 0x3e38aa3b, v20
	v_exp_f32_e32 v19, v19
	v_add_f32_e32 v3, 1.0, v3
	v_mul_f32_e32 v4, 0x3e38aa3b, v4
	v_exp_f32_e32 v4, v4
	v_rcp_f32_e32 v20, v3
	v_add_f32_e32 v3, 1.0, v19
	v_mul_f32_e32 v19, 0x3e38aa3b, v21
	v_exp_f32_e32 v19, v19
	v_mul_f32_e32 v5, 0x3e38aa3b, v5
	v_exp_f32_e32 v5, v5
	v_add_f32_e32 v4, 1.0, v4
	v_rcp_f32_e32 v67, v4
	v_add_f32_e32 v4, 1.0, v19
	v_rcp_f32_e32 v19, v4
	v_add_f32_e32 v4, 1.0, v5
	v_mul_f32_e32 v5, 0x3e38aa3b, v22
	v_mul_f32_e32 v6, 0x3e38aa3b, v6
	v_exp_f32_e32 v5, v5
	v_exp_f32_e32 v6, v6
	v_rcp_f32_e32 v21, v4
	v_mul_f32_e32 v7, 0x3e38aa3b, v7
	v_add_f32_e32 v4, 1.0, v5
	v_add_f32_e32 v5, 1.0, v6
	v_mul_f32_e32 v6, 0x3e38aa3b, v23
	v_exp_f32_e32 v6, v6
	v_exp_f32_e32 v7, v7
	v_rcp_f32_e32 v22, v5
	v_mul_f32_e32 v8, 0x3e38aa3b, v8
	v_add_f32_e32 v5, 1.0, v6
	v_rcp_f32_e32 v6, v5
	v_add_f32_e32 v5, 1.0, v7
	v_mul_f32_e32 v7, 0x3e38aa3b, v24
	v_exp_f32_e32 v7, v7
	v_exp_f32_e32 v8, v8
	v_rcp_f32_e32 v24, v5
	v_mul_f32_e32 v9, 0x3e38aa3b, v9
	v_add_f32_e32 v5, 1.0, v7
	v_add_f32_e32 v7, 1.0, v8
	v_mul_f32_e32 v8, 0x3e38aa3b, v25
	v_exp_f32_e32 v8, v8
	v_exp_f32_e32 v9, v9
	v_rcp_f32_e32 v23, v7
	v_mul_f32_e32 v10, 0x3e38aa3b, v10
	v_add_f32_e32 v7, 1.0, v8
	v_add_f32_e32 v8, 1.0, v9
	v_mul_f32_e32 v9, 0x3e38aa3b, v26
	v_exp_f32_e32 v9, v9
	v_exp_f32_e32 v10, v10
	v_rcp_f32_e32 v25, v8
	v_mul_f32_e32 v11, 0x3e38aa3b, v11
	v_add_f32_e32 v8, 1.0, v9
	v_add_f32_e32 v9, 1.0, v10
	v_mul_f32_e32 v10, 0x3e38aa3b, v27
	v_exp_f32_e32 v10, v10
	v_exp_f32_e32 v11, v11
	v_rcp_f32_e32 v26, v9
	v_mul_f32_e32 v12, 0x3e38aa3b, v12
	v_add_f32_e32 v9, 1.0, v10
	v_rcp_f32_e32 v10, v9
	v_add_f32_e32 v9, 1.0, v11
	v_mul_f32_e32 v11, 0x3e38aa3b, v28
	v_exp_f32_e32 v11, v11
	v_exp_f32_e32 v27, v12
	v_rcp_f32_e32 v12, v9
	v_mul_f32_e32 v14, 0x3e38aa3b, v14
	v_add_f32_e32 v9, 1.0, v11
	v_add_f32_e32 v11, 1.0, v27
	v_mul_f32_e32 v27, 0x3e38aa3b, v29
	v_exp_f32_e32 v28, v27
	v_rcp_f32_e32 v27, v11
	v_exp_f32_e32 v29, v14
	v_mul_f32_e32 v15, 0x3e38aa3b, v15
	v_add_f32_e32 v11, 1.0, v28
	v_mul_f32_e32 v28, 0x3e38aa3b, v30
	v_exp_f32_e32 v28, v28
	v_mul_f32_e32 v13, 0x3e38aa3b, v13
	v_exp_f32_e32 v15, v15
	v_mul_f32_e32 v16, 0x3e38aa3b, v16
	v_add_f32_e32 v14, 1.0, v28
	v_add_f32_e32 v28, 1.0, v29
	v_mul_f32_e32 v29, 0x3e38aa3b, v31
	v_exp_f32_e32 v29, v29
	v_mul_f32_e32 v17, 0x3e38aa3b, v17
	v_exp_f32_e32 v13, v13
	v_exp_f32_e32 v31, v16
	v_add_f32_e32 v29, 1.0, v29
	v_rcp_f32_e32 v30, v29
	v_mul_f32_e32 v29, 0x3e38aa3b, v32
	v_exp_f32_e32 v29, v29
	v_exp_f32_e32 v17, v17
	v_add_f32_e32 v15, 1.0, v15
	v_add_f32_e32 v13, 1.0, v13
	v_rcp_f32_e32 v16, v15
	v_add_f32_e32 v15, 1.0, v29
	v_add_f32_e32 v29, 1.0, v31
	v_add_f32_e32 v17, 1.0, v17
	v_rcp_f32_e32 v13, v13
	v_rcp_f32_e32 v28, v28
	v_rcp_f32_e32 v29, v29
	v_rcp_f32_e32 v17, v17
	v_mul_f32 v80, v26, v12
	v_mul_f32 v81, v27, v13
	v_rcp_f32_e32 v66, v66
	v_mul_f32 v80, v80, v81
	v_mul_f32 v90, v28, v16
	v_mul_f32 v91, v29, v17
	v_mul_f32_e32 v31, 0x3e38aa3b, v33
	v_mul_f32 v90, v90, v91
	v_exp_f32_e32 v31, v31
	v_mov_b32_e32 v81, v90
	s_nop 1
	v_permlane32_swap_b32_e32 v90, v81
	v_mov_b32_e32 v86, v80
	v_fma_f32 v91, v81, v134, v135
	s_nop 0
	v_permlane32_swap_b32_e32 v80, v86
	v_mov_b32_e32 v87, v90
	v_mul_f32_e32 v90, v17, v91
	v_mul_f32 v68, v66, v20
	v_mul_f32 v69, v67, v21
	v_mul_f32 v76, v22, v24
	v_mul_f32 v77, v23, v25
	v_mov_b32_e32 v92, v29
	v_mov_b32_e32 v93, v17
	v_mov_b32_e32 v94, v28
	v_mul_f32_e32 v17, v29, v90
	v_mul_f32 v28, v80, v86
	v_mul_f32 v29, v81, v87
	v_mul_f32 v68, v68, v69
	v_mul_f32 v76, v76, v77
	v_mul_f32 v80, v28, v29
	v_mul_f32 v81, v29, v28
	v_fma_f32 v28, v86, v134, v135
	v_add_f32_e32 v31, 1.0, v31
	v_mov_b32_e32 v69, v76
	v_mul_f32_e32 v29, v28, v29
	v_rcp_f32_e32 v14, v14
	v_rcp_f32_e32 v15, v15
	v_rcp_f32_e32 v31, v31
	v_permlane32_swap_b32_e32 v76, v69
	v_sub_f32 v86, 1.0, v27
	v_sub_f32 v87, 1.0, v13
	v_mul_f32_e32 v28, v13, v29
	v_mul_f32 v86, v86, v28
	v_mul_f32 v87, v87, v29
	v_mul_f32_e32 v13, v27, v28
	v_fma_f32 v28, v69, v134, v135
	v_exp_f32_e32 v18, v18
	v_mul_f32_e32 v29, v28, v80
	v_rcp_f32_e32 v8, v8
	v_rcp_f32_e32 v9, v9
	v_rcp_f32_e32 v11, v11
	v_mov_b32_e32 v72, v68
	v_sub_f32 v92, 1.0, v92
	v_sub_f32 v93, 1.0, v93
	v_mul_f32_e32 v28, v25, v29
	v_permlane32_swap_b32_e32 v68, v72
	v_mul_f32 v88, v14, v30
	v_mul_f32 v89, v15, v31
	v_mul_f32 v92, v92, v90
	v_mul_f32 v93, v93, v91
	v_mov_b32_e32 v90, v26
	v_mul_f32_e32 v73, v69, v76
	v_mov_b32_e32 v26, v23
	v_mul_f32_e32 v23, v23, v28
	v_mul_f32 v88, v88, v89
	v_mov_b32_e32 v89, v88
	v_sub_f32 v26, 1.0, v26
	v_sub_f32 v27, 1.0, v25
	v_mov_b32_e32 v76, v22
	v_mov_b32_e32 v77, v24
	v_mul_f32_e32 v22, v24, v23
	v_mul_f32 v24, v72, v68
	v_mul_f32 v25, v73, v80
	v_add_f32_e32 v18, 1.0, v18
	v_mov_b32_e32 v71, v88
	v_mul_f32 v26, v26, v28
	v_mul_f32 v27, v27, v29
	v_mul_f32 v28, v24, v25
	v_mul_f32 v29, v25, v24
	v_fma_f32 v24, v72, v134, v135
	v_rcp_f32_e32 v18, v18
	v_rcp_f32_e32 v3, v3
	v_rcp_f32_e32 v4, v4
	v_rcp_f32_e32 v5, v5
	v_rcp_f32_e32 v7, v7
	v_mul_f32 v78, v8, v10
	v_mul_f32 v79, v9, v11
	v_permlane32_swap_b32_e32 v88, v71
	v_mul_f32_e32 v25, v24, v25
	v_mul_f32 v78, v78, v79
	v_mul_f32_e32 v24, v21, v25
	v_fma_f32 v29, v71, v134, v135
	v_mov_b32_e32 v84, v78
	v_sub_f32 v76, 1.0, v76
	v_sub_f32 v77, 1.0, v77
	v_sub_f32 v68, 1.0, v67
	v_sub_f32 v69, 1.0, v21
	v_mul_f32_e32 v21, v67, v24
	v_mul_f32_e32 v67, v29, v28
	v_permlane32_swap_b32_e32 v78, v84
	v_mul_f32 v22, v76, v22
	v_mul_f32 v23, v77, v23
	v_mul_f32 v76, v68, v24
	v_mul_f32 v77, v69, v25
	v_mov_b32_e32 v68, v66
	v_mul_f32_e32 v85, v71, v88
	v_mul_f32_e32 v66, v31, v67
	v_mov_b32_e32 v79, v28
	v_mul_f32 v32, v2, v18
	v_mul_f32 v33, v3, v19
	v_mul_f32 v74, v4, v6
	v_mul_f32 v75, v5, v7
	v_sub_f32 v68, 1.0, v68
	v_sub_f32 v69, 1.0, v20
	v_mul_f32_e32 v20, v20, v21
	v_mov_b32_e32 v24, v15
	v_mul_f32_e32 v15, v15, v66
	v_mul_f32 v28, v84, v78
	v_mul_f32 v29, v85, v79
	v_mul_f32 v32, v32, v33
	v_mul_f32 v74, v74, v75
	v_mul_f32 v20, v68, v20
	v_mul_f32 v21, v69, v21
	v_sub_f32 v24, 1.0, v24
	v_sub_f32 v25, 1.0, v31
	v_mov_b32_e32 v68, v14
	v_mov_b32_e32 v69, v30
	v_mul_f32_e32 v14, v30, v15
	v_mul_f32 v30, v28, v29
	v_mul_f32 v31, v29, v28
	v_fma_f32 v28, v84, v134, v135
	v_mov_b32_e32 v33, v74
	v_mul_f32 v24, v24, v66
	v_mul_f32 v25, v25, v67
	v_mul_f32_e32 v29, v28, v29
	v_permlane32_swap_b32_e32 v74, v33
	v_sub_f32 v66, 1.0, v9
	v_sub_f32 v67, 1.0, v11
	v_mul_f32_e32 v28, v11, v29
	v_mul_f32 v72, v66, v28
	v_mul_f32 v73, v67, v29
	v_mul_f32_e32 v9, v9, v28
	v_fma_f32 v28, v33, v134, v135
	v_mul_f32_e32 v29, v28, v30
	v_mov_b32_e32 v70, v32
	v_mov_b32_e32 v66, v8
	v_mov_b32_e32 v67, v10
	v_mul_f32_e32 v28, v7, v29
	v_permlane32_swap_b32_e32 v32, v70
	v_sub_f32 v66, 1.0, v66
	v_sub_f32 v67, 1.0, v67
	v_mul_f32_e32 v8, v10, v9
	v_mul_f32_e32 v71, v33, v74
	v_mov_b32_e32 v10, v5
	v_mul_f32_e32 v5, v5, v28
	v_mul_f32 v8, v66, v8
	v_mul_f32 v9, v67, v9
	v_mov_b32_e32 v11, v7
	v_mov_b32_e32 v66, v4
	v_mov_b32_e32 v67, v6
	v_mul_f32_e32 v4, v6, v5
	v_mul_f32 v6, v70, v32
	v_mul_f32 v7, v71, v30
	v_sub_f32 v10, 1.0, v10
	v_sub_f32 v11, 1.0, v11
	v_mul_f32_e32 v123, v6, v7
	v_fma_f32 v6, v70, v134, v135
	v_mul_f32_e32 v7, v6, v7
	v_mul_f32_e32 v6, v19, v7
	v_mul_f32 v10, v10, v28
	v_mul_f32 v11, v11, v29
	v_mov_b32_e32 v28, v3
	v_mul_f32_e32 v3, v3, v6
	s_mov_b32 s4, 0x1f800000
	v_sub_f32 v94, 1.0, v94
	v_sub_f32 v95, 1.0, v16
	v_mul_f32_e32 v16, v16, v17
	v_sub_f32 v90, 1.0, v90
	v_sub_f32 v91, 1.0, v12
	v_mul_f32_e32 v12, v12, v13
	v_sub_f32 v68, 1.0, v68
	v_sub_f32 v69, 1.0, v69
	v_sub_f32 v66, 1.0, v66
	v_sub_f32 v67, 1.0, v67
	v_sub_f32 v28, 1.0, v28
	v_sub_f32 v29, 1.0, v19
	v_sub_f32 v30, 1.0, v2
	v_sub_f32 v31, 1.0, v18
	v_mul_f32_e32 v2, v18, v3
	v_cmp_gt_f32_e32 vcc, s4, v123
	v_readlane_b32 s6, v255, 3
	v_mul_f32 v16, v94, v16
	v_mul_f32 v17, v95, v17
	v_mul_f32 v12, v90, v12
	v_mul_f32 v13, v91, v13
	v_mul_f32 v14, v68, v14
	v_mul_f32 v15, v69, v15
	v_mul_f32 v4, v66, v4
	v_mul_f32 v5, v67, v5
	v_mul_f32 v28, v28, v6
	v_mul_f32 v29, v29, v7
	v_mul_f32 v2, v30, v2
	v_mul_f32 v3, v31, v3
	s_cmp_eq_u64 vcc, exec
	v_readlane_b32 s7, v255, 4
	s_mov_b32 s94, s67
	s_cselect_b64 s[4:5], -1, 0
	v_cvt_pk_bf16_f32 v66, v2, v3
	v_cvt_pk_bf16_f32 v67, v28, v29
	v_cvt_pk_bf16_f32 v68, v4, v5
	v_cvt_pk_bf16_f32 v69, v10, v11
	v_cvt_pk_bf16_f32 v70, v8, v9
	v_cvt_pk_bf16_f32 v71, v72, v73
	v_cvt_pk_bf16_f32 v72, v14, v15
	v_cvt_pk_bf16_f32 v73, v24, v25
	v_cvt_pk_bf16_f32 v74, v20, v21
	v_cvt_pk_bf16_f32 v75, v76, v77
	v_cvt_pk_bf16_f32 v76, v22, v23
	v_cvt_pk_bf16_f32 v77, v26, v27
	v_cvt_pk_bf16_f32 v78, v12, v13
	v_cvt_pk_bf16_f32 v79, v86, v87
	v_cvt_pk_bf16_f32 v80, v16, v17
	s_andn2_b64 vcc, exec, s[6:7]
	v_cvt_pk_bf16_f32 v81, v92, v93
	s_cbranch_vccnz .LBB0_350
	v_mfma_f32_32x32x16_bf16 v[18:33], v[34:37], v[66:69], 0
	s_mov_b64 s[72:73], 0
	s_waitcnt lgkmcnt(10)
	v_mfma_f32_32x32x16_bf16 v[2:17], v[38:41], v[66:69], 0
	v_mfma_f32_32x32x16_bf16 v[18:33], v[42:45], v[70:73], v[18:33]
	s_waitcnt lgkmcnt(8)
	v_mfma_f32_32x32x16_bf16 v[2:17], v[46:49], v[70:73], v[2:17]
	s_waitcnt lgkmcnt(6)
	v_mfma_f32_32x32x16_bf16 v[18:33], v[50:53], v[74:77], v[18:33]
	s_waitcnt lgkmcnt(2)
	v_mfma_f32_32x32x16_bf16 v[2:17], v[54:57], v[74:77], v[2:17]
	v_mfma_f32_32x32x16_bf16 v[18:33], v[58:61], v[78:81], v[18:33]
	s_waitcnt lgkmcnt(0)
	v_mfma_f32_32x32x16_bf16 v[2:17], v[62:65], v[78:81], v[2:17]
	s_branch .LBB0_351

.LBB0_370:
	v_mul_f32_e32 v82, 0x3e38aa3b, v82
	v_exp_f32_e32 v82, v82
	s_nop 7
	v_mul_f32_e32 v66, 0x3e38aa3b, v66
	v_exp_f32_e32 v66, v66
	v_mul_f32_e32 v67, 0x3e38aa3b, v67
	v_add_f32_e32 v82, 1.0, v82
	v_exp_f32_e32 v67, v67
	v_add_f32_e32 v122, 1.0, v66
	v_rcp_f32_e32 v66, v82
	v_mul_f32_e32 v82, 0x3e38aa3b, v83
	v_mul_f32_e32 v83, 0x3e38aa3b, v84
	v_exp_f32_e32 v83, v83
	v_add_f32_e32 v67, 1.0, v67
	v_mul_f32_e32 v68, 0x3e38aa3b, v68
	v_exp_f32_e32 v68, v68
	v_rcp_f32_e32 v84, v67
	v_add_f32_e32 v67, 1.0, v83
	v_mul_f32_e32 v83, 0x3e38aa3b, v85
	v_exp_f32_e32 v83, v83
	v_mul_f32_e32 v69, 0x3e38aa3b, v69
	v_exp_f32_e32 v69, v69
	v_add_f32_e32 v68, 1.0, v68
	v_rcp_f32_e32 v125, v68
	v_add_f32_e32 v68, 1.0, v83
	v_rcp_f32_e32 v83, v68
	v_add_f32_e32 v68, 1.0, v69
	v_mul_f32_e32 v69, 0x3e38aa3b, v86
	v_mul_f32_e32 v70, 0x3e38aa3b, v70
	v_exp_f32_e32 v69, v69
	v_exp_f32_e32 v70, v70
	v_rcp_f32_e32 v85, v68
	v_mul_f32_e32 v71, 0x3e38aa3b, v71
	v_add_f32_e32 v68, 1.0, v69
	v_add_f32_e32 v69, 1.0, v70
	v_mul_f32_e32 v70, 0x3e38aa3b, v87
	v_exp_f32_e32 v70, v70
	v_exp_f32_e32 v71, v71
	v_rcp_f32_e32 v86, v69
	v_mul_f32_e32 v72, 0x3e38aa3b, v72
	v_add_f32_e32 v69, 1.0, v70
	v_rcp_f32_e32 v70, v69
	v_add_f32_e32 v69, 1.0, v71
	v_mul_f32_e32 v71, 0x3e38aa3b, v88
	v_exp_f32_e32 v71, v71
	v_exp_f32_e32 v72, v72
	v_rcp_f32_e32 v88, v69
	v_mul_f32_e32 v73, 0x3e38aa3b, v73
	v_add_f32_e32 v69, 1.0, v71
	v_add_f32_e32 v71, 1.0, v72
	v_mul_f32_e32 v72, 0x3e38aa3b, v89
	v_exp_f32_e32 v72, v72
	v_exp_f32_e32 v73, v73
	v_rcp_f32_e32 v87, v71
	v_mul_f32_e32 v74, 0x3e38aa3b, v74
	v_add_f32_e32 v71, 1.0, v72
	v_add_f32_e32 v72, 1.0, v73
	v_mul_f32_e32 v73, 0x3e38aa3b, v90
	v_exp_f32_e32 v73, v73
	v_exp_f32_e32 v74, v74
	v_rcp_f32_e32 v89, v72
	v_mul_f32_e32 v75, 0x3e38aa3b, v75
	v_add_f32_e32 v72, 1.0, v73
	v_add_f32_e32 v73, 1.0, v74
	v_mul_f32_e32 v74, 0x3e38aa3b, v91
	v_exp_f32_e32 v74, v74
	v_exp_f32_e32 v75, v75
	v_rcp_f32_e32 v90, v73
	v_mul_f32_e32 v76, 0x3e38aa3b, v76
	v_add_f32_e32 v73, 1.0, v74
	v_rcp_f32_e32 v74, v73
	v_add_f32_e32 v73, 1.0, v75
	v_mul_f32_e32 v75, 0x3e38aa3b, v92
	v_exp_f32_e32 v75, v75
	v_exp_f32_e32 v91, v76
	v_rcp_f32_e32 v76, v73
	v_mul_f32_e32 v78, 0x3e38aa3b, v78
	v_add_f32_e32 v73, 1.0, v75
	v_add_f32_e32 v75, 1.0, v91
	v_mul_f32_e32 v91, 0x3e38aa3b, v93
	v_exp_f32_e32 v92, v91
	v_rcp_f32_e32 v91, v75
	v_exp_f32_e32 v93, v78
	v_mul_f32_e32 v79, 0x3e38aa3b, v79
	v_add_f32_e32 v75, 1.0, v92
	v_mul_f32_e32 v92, 0x3e38aa3b, v94
	v_exp_f32_e32 v92, v92
	v_exp_f32_e32 v79, v79
	v_mul_f32_e32 v80, 0x3e38aa3b, v80
	v_mul_f32_e32 v81, 0x3e38aa3b, v81
	v_add_f32_e32 v78, 1.0, v92
	v_add_f32_e32 v92, 1.0, v93
	v_mul_f32_e32 v93, 0x3e38aa3b, v95
	v_exp_f32_e32 v93, v93
	v_exp_f32_e32 v95, v80
	v_exp_f32_e32 v81, v81
	v_mul_f32_e32 v77, 0x3e38aa3b, v77
	v_add_f32_e32 v93, 1.0, v93
	v_rcp_f32_e32 v94, v93
	v_mul_f32_e32 v93, 0x3e38aa3b, v96
	v_exp_f32_e32 v93, v93
	v_exp_f32_e32 v77, v77
	v_add_f32_e32 v79, 1.0, v79
	v_rcp_f32_e32 v80, v79
	v_add_f32_e32 v79, 1.0, v93
	v_add_f32_e32 v93, 1.0, v95
	v_add_f32_e32 v81, 1.0, v81
	v_rcp_f32_e32 v92, v92
	v_rcp_f32_e32 v93, v93
	v_rcp_f32_e32 v81, v81
	v_add_f32_e32 v77, 1.0, v77
	v_rcp_f32_e32 v77, v77
	v_rcp_f32_e32 v124, v122
	v_mul_f32 v180, v92, v80
	v_mul_f32 v181, v93, v81
	v_mov_b32_e32 v182, v93
	v_mul_f32 v180, v180, v181
	v_mul_f32 v148, v90, v76
	v_mul_f32 v149, v91, v77
	v_mov_b32_e32 v141, v180
	v_mul_f32 v148, v148, v149
	v_mov_b32_e32 v149, v148
	s_nop 0
	v_permlane32_swap_b32_e32 v180, v141
	v_mul_f32_e32 v149, v141, v180
	v_fma_f32 v141, v141, v134, v135
	v_mov_b32_e32 v122, v148
	v_mul_f32_e32 v181, v123, v141
	s_nop 0
	v_permlane32_swap_b32_e32 v148, v122
	v_mul_f32_e32 v180, v81, v181
	v_mov_b32_e32 v183, v81
	v_mov_b32_e32 v184, v92
	v_mul_f32_e32 v81, v93, v180
	v_mul_f32 v92, v122, v148
	v_mul_f32 v93, v123, v149
	v_mul_f32_e32 v95, 0x3e38aa3b, v97
	v_mul_f32 v136, v124, v84
	v_mul_f32 v137, v125, v85
	v_mul_f32 v144, v86, v88
	v_mul_f32 v145, v87, v89
	v_mul_f32 v148, v92, v93
	v_mul_f32 v149, v93, v92
	v_fma_f32 v92, v122, v134, v135
	v_exp_f32_e32 v95, v95
	v_mul_f32 v136, v136, v137
	v_mul_f32 v144, v144, v145
	v_mul_f32_e32 v93, v92, v93
	v_mov_b32_e32 v137, v144
	v_sub_f32 v182, 1.0, v182
	v_sub_f32 v183, 1.0, v183
	v_sub_f32 v122, 1.0, v91
	v_sub_f32 v123, 1.0, v77
	v_mul_f32_e32 v92, v77, v93
	v_permlane32_swap_b32_e32 v144, v137
	v_mul_f32 v182, v182, v180
	v_mul_f32 v183, v183, v181
	v_mul_f32 v180, v122, v92
	v_mul_f32 v181, v123, v93
	v_mul_f32_e32 v77, v91, v92
	v_sub_f32 v122, 1.0, v90
	v_sub_f32 v123, 1.0, v76
	v_mul_f32_e32 v76, v76, v77
	v_fma_f32 v92, v137, v134, v135
	v_add_f32_e32 v95, 1.0, v95
	v_mul_f32 v90, v122, v76
	v_mul_f32 v91, v123, v77
	v_mul_f32_e32 v93, v92, v148
	v_rcp_f32_e32 v78, v78
	v_rcp_f32_e32 v79, v79
	v_rcp_f32_e32 v95, v95
	v_sub_f32 v76, 1.0, v87
	v_sub_f32 v77, 1.0, v89
	v_mul_f32_e32 v92, v89, v93
	v_mov_b32_e32 v140, v136
	v_mul_f32_e32 v141, v137, v144
	v_mul_f32 v144, v76, v92
	v_mul_f32 v145, v77, v93
	v_mul_f32_e32 v87, v87, v92
	v_exp_f32_e32 v82, v82
	v_permlane32_swap_b32_e32 v136, v140
	v_sub_f32 v76, 1.0, v86
	v_sub_f32 v77, 1.0, v88
	v_mul_f32_e32 v86, v88, v87
	v_rcp_f32_e32 v72, v72
	v_rcp_f32_e32 v73, v73
	v_rcp_f32_e32 v75, v75
	v_mul_f32 v76, v76, v86
	v_mul_f32 v77, v77, v87
	v_mul_f32 v86, v140, v136
	v_mul_f32 v87, v141, v148
	v_mul_f32 v178, v78, v94
	v_mul_f32 v179, v79, v95
	v_mul_f32 v88, v86, v87
	v_mul_f32 v89, v87, v86
	v_fma_f32 v86, v140, v134, v135
	v_mul_f32 v178, v178, v179
	v_mul_f32_e32 v87, v86, v87
	v_add_f32_e32 v82, 1.0, v82
	v_mov_b32_e32 v139, v178
	v_mul_f32_e32 v86, v85, v87
	v_rcp_f32_e32 v82, v82
	v_rcp_f32_e32 v67, v67
	v_rcp_f32_e32 v68, v68
	v_rcp_f32_e32 v69, v69
	v_rcp_f32_e32 v71, v71
	v_mul_f32 v146, v72, v74
	v_mul_f32 v147, v73, v75
	v_permlane32_swap_b32_e32 v178, v139
	v_mov_b32_e32 v93, v85
	v_mul_f32_e32 v85, v125, v86
	v_mul_f32 v146, v146, v147
	v_sub_f32 v122, 1.0, v124
	v_sub_f32 v123, 1.0, v84
	v_mul_f32_e32 v84, v84, v85
	v_fma_f32 v89, v139, v134, v135
	v_mov_b32_e32 v150, v146
	v_mul_f32 v84, v122, v84
	v_mul_f32 v85, v123, v85
	v_mul_f32_e32 v123, v89, v88
	v_permlane32_swap_b32_e32 v146, v150
	v_sub_f32 v92, 1.0, v125
	v_sub_f32 v93, 1.0, v93
	v_mul_f32_e32 v151, v139, v178
	v_mul_f32_e32 v122, v95, v123
	v_mov_b32_e32 v147, v88
	v_mul_f32 v96, v66, v82
	v_mul_f32 v97, v67, v83
	v_mul_f32 v142, v68, v70
	v_mul_f32 v143, v69, v71
	v_mul_f32 v92, v92, v86
	v_mul_f32 v93, v93, v87
	v_mov_b32_e32 v86, v79
	v_mul_f32_e32 v79, v79, v122
	v_mul_f32 v88, v150, v146
	v_mul_f32 v89, v151, v147
	v_mul_f32 v96, v96, v97
	v_mul_f32 v142, v142, v143
	v_sub_f32 v86, 1.0, v86
	v_sub_f32 v87, 1.0, v95
	v_mov_b32_e32 v124, v78
	v_mov_b32_e32 v125, v94
	v_mul_f32_e32 v78, v94, v79
	v_mul_f32 v94, v88, v89
	v_mul_f32 v95, v89, v88
	v_fma_f32 v88, v150, v134, v135
	v_mov_b32_e32 v97, v142
	v_mul_f32 v86, v86, v122
	v_mul_f32 v87, v87, v123
	v_mul_f32_e32 v89, v88, v89
	v_permlane32_swap_b32_e32 v142, v97
	v_sub_f32 v124, 1.0, v124
	v_sub_f32 v125, 1.0, v125
	v_sub_f32 v122, 1.0, v73
	v_sub_f32 v123, 1.0, v75
	v_mul_f32_e32 v88, v75, v89
	v_mul_f32 v78, v124, v78
	v_mul_f32 v79, v125, v79
	v_mul_f32 v124, v122, v88
	v_mul_f32 v125, v123, v89
	v_mul_f32_e32 v73, v73, v88
	v_fma_f32 v88, v97, v134, v135
	v_mov_b32_e32 v123, v74
	v_mul_f32_e32 v89, v88, v94
	v_mov_b32_e32 v138, v96
	v_sub_f32 v122, 1.0, v72
	v_sub_f32 v123, 1.0, v123
	v_mul_f32_e32 v72, v74, v73
	v_mul_f32_e32 v88, v71, v89
	v_permlane32_swap_b32_e32 v96, v138
	v_mul_f32 v72, v122, v72
	v_mul_f32 v73, v123, v73
	v_mul_f32_e32 v139, v97, v142
	v_mov_b32_e32 v74, v69
	v_mul_f32_e32 v69, v69, v88
	v_mov_b32_e32 v97, v94
	v_mov_b32_e32 v75, v71
	v_sub_f32 v122, 1.0, v68
	v_sub_f32 v123, 1.0, v70
	v_mul_f32_e32 v68, v70, v69
	v_mul_f32 v70, v138, v96
	v_mul_f32 v71, v139, v97
	v_mul_f32 v68, v122, v68
	v_mul_f32 v69, v123, v69
	v_mul_f32_e32 v123, v70, v71
	v_fma_f32 v70, v138, v134, v135
	v_mul_f32_e32 v71, v70, v71
	v_sub_f32 v74, 1.0, v74
	v_sub_f32 v75, 1.0, v75
	v_mul_f32_e32 v70, v83, v71
	v_mul_f32 v74, v74, v88
	v_mul_f32 v75, v75, v89
	v_mov_b32_e32 v88, v67
	v_mul_f32_e32 v67, v67, v70
	s_mov_b32 s72, 0x1f800000
	v_sub_f32 v184, 1.0, v184
	v_sub_f32 v185, 1.0, v80
	v_mul_f32_e32 v80, v80, v81
	v_sub_f32 v88, 1.0, v88
	v_sub_f32 v89, 1.0, v83
	v_sub_f32 v94, 1.0, v66
	v_sub_f32 v95, 1.0, v82
	v_mul_f32_e32 v66, v82, v67
	v_cmp_gt_f32_e32 vcc, s72, v123
	v_readlane_b32 s72, v255, 3
	v_mul_f32 v80, v184, v80
	v_mul_f32 v81, v185, v81
	v_mul_f32 v88, v88, v70
	v_mul_f32 v89, v89, v71
	v_mul_f32 v66, v94, v66
	v_mul_f32 v67, v95, v67
	s_cmp_eq_u64 vcc, exec
	v_readlane_b32 s73, v255, 4
	s_cselect_b64 s[84:85], -1, 0
	v_cvt_pk_bf16_f32 v66, v66, v67
	v_cvt_pk_bf16_f32 v67, v88, v89
	v_cvt_pk_bf16_f32 v68, v68, v69
	v_cvt_pk_bf16_f32 v69, v74, v75
	v_cvt_pk_bf16_f32 v70, v72, v73
	v_cvt_pk_bf16_f32 v71, v124, v125
	v_cvt_pk_bf16_f32 v72, v78, v79
	v_cvt_pk_bf16_f32 v73, v86, v87
	v_cvt_pk_bf16_f32 v74, v84, v85
	v_cvt_pk_bf16_f32 v75, v92, v93
	v_cvt_pk_bf16_f32 v76, v76, v77
	v_cvt_pk_bf16_f32 v77, v144, v145
	v_cvt_pk_bf16_f32 v78, v90, v91
	v_cvt_pk_bf16_f32 v79, v180, v181
	v_cvt_pk_bf16_f32 v80, v80, v81
	v_cvt_pk_bf16_f32 v81, v182, v183
	s_andn2_b64 vcc, exec, s[72:73]
	s_mov_b64 s[72:73], -1
	s_cbranch_vccnz .LBB0_372
	v_mfma_f32_32x32x16_bf16 v[18:33], v[34:37], v[66:69], v[18:33]
	s_mov_b64 s[72:73], 0
	s_waitcnt lgkmcnt(10)
	v_mfma_f32_32x32x16_bf16 v[2:17], v[38:41], v[66:69], v[2:17]
	v_mfma_f32_32x32x16_bf16 v[18:33], v[42:45], v[70:73], v[18:33]
	s_waitcnt lgkmcnt(8)
	v_mfma_f32_32x32x16_bf16 v[2:17], v[46:49], v[70:73], v[2:17]
	s_waitcnt lgkmcnt(6)
	v_mfma_f32_32x32x16_bf16 v[18:33], v[50:53], v[74:77], v[18:33]
	s_waitcnt lgkmcnt(2)
	v_mfma_f32_32x32x16_bf16 v[2:17], v[54:57], v[74:77], v[2:17]
	v_mfma_f32_32x32x16_bf16 v[18:33], v[58:61], v[78:81], v[18:33]
	s_waitcnt lgkmcnt(0)
	v_mfma_f32_32x32x16_bf16 v[2:17], v[62:65], v[78:81], v[2:17]

.LBB0_384:
	s_or_b64 exec, exec, s[4:5]
	v_lshl_add_u64 v[34:35], v[120:121], 1, s[2:3]
	s_waitcnt lgkmcnt(9)
	v_lshlrev_b64 v[46:47], 1, v[114:115]
	v_lshl_add_u64 v[34:35], v[34:35], 0, v[46:47]
	s_mov_b64 s[2:3], 0x3000000
	v_lshl_add_u64 v[36:37], v[34:35], 0, s[2:3]
	v_add_co_u32_e32 v34, vcc, 0x3000000, v34
	v_readlane_b32 s2, v255, 49
	s_nop 0
	v_addc_co_u32_e32 v35, vcc, 0, v35, vcc
	s_waitcnt lgkmcnt(7)
	s_nop 0
	v_lshl_add_u32 v0, s2, 11, v0
	s_waitcnt lgkmcnt(6)
	v_lshlrev_b64 v[52:53], 11, v[0:1]
	v_readlane_b32 s2, v255, 50
	v_lshl_add_u64 v[52:53], s[56:57], 0, v[52:53]
	s_lshl_b32 s80, s2, 7
	v_lshl_add_u64 v[52:53], v[52:53], 0, s[80:81]
	v_lshl_add_u64 v[46:47], v[52:53], 0, v[46:47]
	s_waitcnt lgkmcnt(0)
	s_barrier
	v_mov_b32_e32 v48, v192
	v_mov_b32_e32 v49, v193
	v_mov_b32_e32 v42, v218
	v_mov_b32_e32 v43, v219
	v_mov_b32_e32 v44, v220
	v_mov_b32_e32 v45, v221
	v_mov_b32_e32 v38, v222
	v_mov_b32_e32 v39, v223
	v_mov_b32_e32 v40, v224
	v_mov_b32_e32 v41, v225
	v_mov_b32_e32 v34, v240
	v_mov_b32_e32 v35, v241
	v_mov_b32_e32 v36, v242
	v_mov_b32_e32 v37, v243
	s_mov_b64 s[2:3], 0
	v_mov_b32_e32 v0, v194
	s_nop 1
	v_permlane32_swap_b32_e32 v48, v0
	v_lshlrev_b32_e32 v50, 16, v48
	s_waitcnt lgkmcnt(3)
	v_mov_b32_e32 v54, v195
	v_and_b32_e32 v51, 0xffff0000, v48
	v_mul_f32_e32 v48, 0xbfb8aa3b, v50
	v_exp_f32_e32 v48, v48
	v_permlane32_swap_b32_e32 v49, v54
	v_add_f32_e32 v48, 1.0, v48
	v_rcp_f32_e32 v52, v48
	v_mul_f32_e32 v48, 0xbfb8aa3b, v51
	v_exp_f32_e32 v48, v48
	s_nop 0
	v_add_f32_e32 v48, 1.0, v48
	v_rcp_f32_e32 v53, v48
	v_lshlrev_b32_e32 v48, 16, v49
	v_and_b32_e32 v49, 0xffff0000, v49
	v_mul_f32 v50, v52, v50
	v_mul_f32 v51, v53, v51
	s_nop 0
	v_mul_f32 v18, v18, v50
	v_mul_f32 v19, v19, v51
	s_nop 0
	v_cvt_pk_bf16_f32 v18, v18, v19
	v_mul_f32_e32 v19, 0xbfb8aa3b, v48
	v_exp_f32_e32 v19, v19
	s_nop 0
	v_add_f32_e32 v19, 1.0, v19
	v_rcp_f32_e32 v50, v19
	v_mul_f32_e32 v19, 0xbfb8aa3b, v49
	v_exp_f32_e32 v19, v19
	s_nop 0
	v_add_f32_e32 v19, 1.0, v19
	v_rcp_f32_e32 v51, v19
	s_nop 0
	v_mul_f32 v48, v50, v48
	v_mul_f32 v49, v51, v49
	s_nop 0
	v_mul_f32 v20, v20, v48
	v_mul_f32 v21, v21, v49
	s_nop 0
	v_cvt_pk_bf16_f32 v19, v20, v21
	v_lshlrev_b32_e32 v20, 16, v0
	v_and_b32_e32 v21, 0xffff0000, v0
	v_mul_f32_e32 v0, 0xbfb8aa3b, v20
	v_exp_f32_e32 v0, v0
	s_nop 0
	v_add_f32_e32 v0, 1.0, v0
	v_rcp_f32_e32 v48, v0
	v_mul_f32_e32 v0, 0xbfb8aa3b, v21
	v_exp_f32_e32 v0, v0
	s_nop 0
	v_add_f32_e32 v0, 1.0, v0
	v_rcp_f32_e32 v49, v0
	s_nop 0
	v_mul_f32 v20, v48, v20
	v_mul_f32 v21, v49, v21
	s_nop 0
	v_mul_f32 v20, v22, v20
	v_mul_f32 v21, v23, v21
	v_lshlrev_b32_e32 v22, 16, v54
	v_mul_f32_e32 v0, 0xbfb8aa3b, v22
	v_exp_f32_e32 v0, v0
	v_and_b32_e32 v23, 0xffff0000, v54
	v_cvt_pk_bf16_f32 v20, v20, v21
	s_nop 1
	v_permlane32_swap_b32_e32 v18, v20
	v_add_f32_e32 v0, 1.0, v0
	v_rcp_f32_e32 v48, v0
	v_mul_f32_e32 v0, 0xbfb8aa3b, v23
	v_exp_f32_e32 v0, v0
	s_nop 0
	v_add_f32_e32 v0, 1.0, v0
	v_rcp_f32_e32 v49, v0
	v_mov_b32_e32 v0, v44
	s_nop 1
	v_permlane32_swap_b32_e32 v42, v0
	v_mul_f32 v22, v48, v22
	v_mul_f32 v23, v49, v23
	s_nop 0
	v_mul_f32 v22, v24, v22
	v_mul_f32 v23, v25, v23
	s_nop 0
	v_cvt_pk_bf16_f32 v21, v22, v23
	s_nop 1
	v_permlane32_swap_b32_e32 v19, v21
	global_store_dwordx4 v[46:47], v[18:21], off
	v_mov_b32_e32 v22, v45
	s_nop 1
	v_permlane32_swap_b32_e32 v43, v22
	v_lshlrev_b32_e32 v18, 16, v42
	v_and_b32_e32 v19, 0xffff0000, v42
	v_mul_f32_e32 v20, 0xbfb8aa3b, v18
	v_mul_f32_e32 v21, 0xbfb8aa3b, v19
	v_exp_f32_e32 v20, v20
	v_exp_f32_e32 v21, v21
	v_add_f32_e32 v20, 1.0, v20
	v_add_f32_e32 v21, 1.0, v21
	v_rcp_f32_e32 v20, v20
	v_rcp_f32_e32 v21, v21
	s_nop 0
	v_mul_f32 v18, v20, v18
	v_mul_f32 v19, v21, v19
	s_nop 0
	v_mul_f32 v2, v2, v18
	v_mul_f32 v3, v3, v19
	v_lshlrev_b32_e32 v18, 16, v43
	v_cvt_pk_bf16_f32 v2, v2, v3
	v_mul_f32_e32 v3, 0xbfb8aa3b, v18
	v_exp_f32_e32 v3, v3
	v_and_b32_e32 v19, 0xffff0000, v43
	v_add_f32_e32 v3, 1.0, v3
	v_rcp_f32_e32 v20, v3
	v_mul_f32_e32 v3, 0xbfb8aa3b, v19
	v_exp_f32_e32 v3, v3
	s_nop 0
	v_add_f32_e32 v3, 1.0, v3
	v_rcp_f32_e32 v21, v3
	s_nop 0
	v_mul_f32 v18, v20, v18
	v_mul_f32 v19, v21, v19
	s_nop 0
	v_mul_f32 v4, v4, v18
	v_mul_f32 v5, v5, v19
	s_nop 0
	v_cvt_pk_bf16_f32 v3, v4, v5
	v_lshlrev_b32_e32 v4, 16, v0
	v_and_b32_e32 v5, 0xffff0000, v0
	v_mul_f32_e32 v0, 0xbfb8aa3b, v4
	v_exp_f32_e32 v0, v0
	s_nop 0
	v_add_f32_e32 v0, 1.0, v0
	v_rcp_f32_e32 v18, v0
	v_mul_f32_e32 v0, 0xbfb8aa3b, v5
	v_exp_f32_e32 v0, v0
	s_nop 0
	v_add_f32_e32 v0, 1.0, v0
	v_rcp_f32_e32 v19, v0
	s_nop 0
	v_mul_f32 v4, v18, v4
	v_mul_f32 v5, v19, v5
	s_nop 0
	v_mul_f32 v4, v6, v4
	v_mul_f32 v5, v7, v5
	v_lshlrev_b32_e32 v6, 16, v22
	v_mul_f32_e32 v0, 0xbfb8aa3b, v6
	v_exp_f32_e32 v0, v0
	v_and_b32_e32 v7, 0xffff0000, v22
	v_cvt_pk_bf16_f32 v4, v4, v5
	s_nop 1
	v_permlane32_swap_b32_e32 v2, v4
	v_add_f32_e32 v0, 1.0, v0
	v_rcp_f32_e32 v18, v0
	v_mul_f32_e32 v0, 0xbfb8aa3b, v7
	v_exp_f32_e32 v0, v0
	s_nop 0
	v_add_f32_e32 v0, 1.0, v0
	v_rcp_f32_e32 v19, v0
	v_mov_b32_e32 v0, v40
	s_nop 1
	v_permlane32_swap_b32_e32 v38, v0
	v_mul_f32 v6, v18, v6
	v_mul_f32 v7, v19, v7
	s_nop 0
	v_mul_f32 v6, v8, v6
	v_mul_f32 v7, v9, v7
	v_mov_b32_e32 v8, v41
	v_cvt_pk_bf16_f32 v5, v6, v7
	s_nop 1
	v_permlane32_swap_b32_e32 v3, v5
	global_store_dwordx4 v[46:47], v[2:5], off offset:64
	v_permlane32_swap_b32_e32 v39, v8
	s_nop 0
	v_lshlrev_b32_e32 v2, 16, v38
	v_and_b32_e32 v3, 0xffff0000, v38
	v_mul_f32_e32 v4, 0xbfb8aa3b, v2
	v_mul_f32_e32 v5, 0xbfb8aa3b, v3
	v_exp_f32_e32 v4, v4
	v_exp_f32_e32 v5, v5
	v_add_f32_e32 v4, 1.0, v4
	v_add_f32_e32 v5, 1.0, v5
	v_rcp_f32_e32 v4, v4
	v_rcp_f32_e32 v5, v5
	s_nop 0
	v_mul_f32 v2, v4, v2
	v_mul_f32 v3, v5, v3
	s_nop 0
	v_mul_f32 v2, v26, v2
	v_mul_f32 v3, v27, v3
	v_lshlrev_b32_e32 v4, 16, v39
	v_cvt_pk_bf16_f32 v2, v2, v3
	v_mul_f32_e32 v3, 0xbfb8aa3b, v4
	v_exp_f32_e32 v3, v3
	v_and_b32_e32 v5, 0xffff0000, v39
	v_add_f32_e32 v3, 1.0, v3
	v_rcp_f32_e32 v6, v3
	v_mul_f32_e32 v3, 0xbfb8aa3b, v5
	v_exp_f32_e32 v3, v3
	s_nop 0
	v_add_f32_e32 v3, 1.0, v3
	v_rcp_f32_e32 v7, v3
	s_nop 0
	v_mul_f32 v4, v6, v4
	v_mul_f32 v5, v7, v5
	s_nop 0
	v_mul_f32 v4, v28, v4
	v_mul_f32 v5, v29, v5
	s_nop 0
	v_cvt_pk_bf16_f32 v3, v4, v5
	v_lshlrev_b32_e32 v4, 16, v0
	v_and_b32_e32 v5, 0xffff0000, v0
	v_mul_f32_e32 v0, 0xbfb8aa3b, v4
	v_exp_f32_e32 v0, v0
	s_nop 0
	v_add_f32_e32 v0, 1.0, v0
	v_rcp_f32_e32 v6, v0
	v_mul_f32_e32 v0, 0xbfb8aa3b, v5
	v_exp_f32_e32 v0, v0
	s_nop 0
	v_add_f32_e32 v0, 1.0, v0
	v_rcp_f32_e32 v7, v0
	s_nop 0
	v_mul_f32 v4, v6, v4
	v_mul_f32 v5, v7, v5
	v_lshlrev_b32_e32 v6, 16, v8
	v_mul_f32_e32 v0, 0xbfb8aa3b, v6
	v_exp_f32_e32 v0, v0
	v_and_b32_e32 v7, 0xffff0000, v8
	v_mul_f32 v4, v30, v4
	v_mul_f32 v5, v31, v5
	v_add_f32_e32 v0, 1.0, v0
	v_rcp_f32_e32 v8, v0
	v_mul_f32_e32 v0, 0xbfb8aa3b, v7
	v_exp_f32_e32 v0, v0
	v_cvt_pk_bf16_f32 v4, v4, v5
	s_nop 1
	v_permlane32_swap_b32_e32 v2, v4
	v_add_f32_e32 v0, 1.0, v0
	v_rcp_f32_e32 v9, v0
	v_mov_b32_e32 v0, v36
	s_nop 1
	v_permlane32_swap_b32_e32 v34, v0
	v_mul_f32 v6, v8, v6
	v_mul_f32 v7, v9, v7
	v_mov_b32_e32 v8, v37
	v_mul_f32 v6, v32, v6
	v_mul_f32 v7, v33, v7
	s_nop 0
	v_permlane32_swap_b32_e32 v35, v8
	v_cvt_pk_bf16_f32 v5, v6, v7
	s_nop 1
	v_permlane32_swap_b32_e32 v3, v5
	global_store_dwordx4 v[46:47], v[2:5], off offset:32
	s_nop 1
	v_lshlrev_b32_e32 v2, 16, v34
	v_and_b32_e32 v3, 0xffff0000, v34
	v_mul_f32_e32 v4, 0xbfb8aa3b, v2
	v_mul_f32_e32 v5, 0xbfb8aa3b, v3
	v_exp_f32_e32 v4, v4
	v_exp_f32_e32 v5, v5
	v_add_f32_e32 v4, 1.0, v4
	v_add_f32_e32 v5, 1.0, v5
	v_rcp_f32_e32 v4, v4
	v_rcp_f32_e32 v5, v5
	s_nop 0
	v_mul_f32 v2, v4, v2
	v_mul_f32 v3, v5, v3
	s_nop 0
	v_mul_f32 v2, v10, v2
	v_mul_f32 v3, v11, v3
	v_lshlrev_b32_e32 v4, 16, v35
	v_cvt_pk_bf16_f32 v2, v2, v3
	v_mul_f32_e32 v3, 0xbfb8aa3b, v4
	v_exp_f32_e32 v3, v3
	v_and_b32_e32 v5, 0xffff0000, v35
	v_add_f32_e32 v3, 1.0, v3
	v_rcp_f32_e32 v6, v3
	v_mul_f32_e32 v3, 0xbfb8aa3b, v5
	v_exp_f32_e32 v3, v3
	s_nop 0
	v_add_f32_e32 v3, 1.0, v3
	v_rcp_f32_e32 v7, v3
	s_nop 0
	v_mul_f32 v4, v6, v4
	v_mul_f32 v5, v7, v5
	s_nop 0
	v_mul_f32 v4, v12, v4
	v_mul_f32 v5, v13, v5
	s_nop 0
	v_cvt_pk_bf16_f32 v3, v4, v5
	v_lshlrev_b32_e32 v4, 16, v0
	v_and_b32_e32 v5, 0xffff0000, v0
	v_mul_f32_e32 v0, 0xbfb8aa3b, v4
	v_exp_f32_e32 v0, v0
	s_nop 0
	v_add_f32_e32 v0, 1.0, v0
	v_rcp_f32_e32 v6, v0
	v_mul_f32_e32 v0, 0xbfb8aa3b, v5
	v_exp_f32_e32 v0, v0
	s_nop 0
	v_add_f32_e32 v0, 1.0, v0
	v_rcp_f32_e32 v7, v0
	s_nop 0
	v_mul_f32 v4, v6, v4
	v_mul_f32 v5, v7, v5
	v_lshlrev_b32_e32 v6, 16, v8
	v_mul_f32_e32 v0, 0xbfb8aa3b, v6
	v_exp_f32_e32 v0, v0
	v_and_b32_e32 v7, 0xffff0000, v8
	v_mul_f32 v4, v14, v4
	v_mul_f32 v5, v15, v5
	v_add_f32_e32 v0, 1.0, v0
	v_rcp_f32_e32 v8, v0
	v_mul_f32_e32 v0, 0xbfb8aa3b, v7
	v_exp_f32_e32 v0, v0
	v_cvt_pk_bf16_f32 v4, v4, v5
	s_nop 1
	v_permlane32_swap_b32_e32 v2, v4
	v_add_f32_e32 v0, 1.0, v0
	v_rcp_f32_e32 v9, v0
	s_nop 0
	v_mul_f32 v6, v8, v6
	v_mul_f32 v7, v9, v7
	s_nop 0
	v_mul_f32 v6, v16, v6
	v_mul_f32 v7, v17, v7
	s_nop 0
	v_cvt_pk_bf16_f32 v5, v6, v7
	s_nop 1
	v_permlane32_swap_b32_e32 v3, v5
	global_store_dwordx4 v[46:47], v[2:5], off offset:96
	s_waitcnt vmcnt(4)
	v_min_u32_e32 v253, 0xffff, v253
	v_or_b32_e32 v95, v95, v253
